# v14 + next-unit Q rows prefetched to cache in attention unit prologue
# baseline (speedup 1.0000x reference)
.LBB0_741:
	v_mov_b32_e32 v195, v193
	s_lshl_b32 s10, s4, 8
	v_readfirstlane_b32 s8, v195
	s_movk_i32 s4, 0xffc0
	s_and_b32 s11, s8, 0xffffffc0
	v_mov_b32_e32 v0, s8
	v_bfi_b32 v0, s4, v0, v195
	v_mul_hi_i32 v1, v0, s69
	v_lshrrev_b32_e32 v2, 31, v1
	v_ashrrev_i32_e32 v1, 2, v1
	s_lshl_b32 s9, s11, 2
	v_add_u32_e32 v1, v1, v2
	s_ashr_i32 s42, s8, 6
	s_add_i32 s48, s9, 0
	v_mad_u64_u32 v[2:3], s[8:9], v1, s1, v[0:1]
	v_lshrrev_b32_e32 v3, 1, v1
	v_bitop3_b32 v2, v2, v3, 7 bitop3:0x78
	v_mul_lo_u32 v1, v1, s47
	v_lshl_add_u32 v180, v2, 3, v1
	v_add_u32_e32 v2, 0x200, v0
	v_mul_hi_i32 v1, v2, s69
	v_lshrrev_b32_e32 v3, 31, v1
	v_ashrrev_i32_e32 v1, 2, v1
	v_add_u32_e32 v1, v1, v3
	v_mad_u64_u32 v[2:3], s[8:9], v1, s1, v[2:3]
	v_lshrrev_b32_e32 v3, 1, v1
	v_bitop3_b32 v2, v2, v3, 7 bitop3:0x78
	v_mul_lo_u32 v1, v1, s47
	v_lshl_add_u32 v182, v2, 3, v1
	v_add_u32_e32 v2, 0x400, v0
	v_mul_hi_i32 v1, v2, s69
	v_lshrrev_b32_e32 v3, 31, v1
	v_ashrrev_i32_e32 v1, 2, v1
	v_add_u32_e32 v1, v1, v3
	v_mad_u64_u32 v[2:3], s[8:9], v1, s1, v[2:3]
	s_lshl_b32 s39, s42, 5
	v_lshrrev_b32_e32 v3, 1, v1
	v_and_b32_e32 v190, 31, v195
	s_add_i32 s39, s39, s10
	s_cmp_eq_u32 s41, 0
	s_cselect_b32 vcc_lo, s55, s59
	s_cmp_eq_u32 s41, 1
	s_cselect_b32 vcc_lo, s40, vcc_lo
	s_lshl_b32 vcc_lo, vcc_lo, 8
	s_sub_i32 vcc_hi, s39, s10
	s_add_i32 vcc_lo, vcc_lo, vcc_hi
	s_mul_i32 vcc_lo, vcc_lo, 0x180
	v_and_b32_e32 v97, 63, v195
	v_lshl_add_u32 v97, v97, 6, vcc_lo
	global_load_dword v96, v97, s[80:81]
	v_add_u32_e32 v97, 0x1000, v97
	global_load_dword v96, v97, s[80:81]
	v_add_u32_e32 v97, 0x1000, v97
	global_load_dword v96, v97, s[80:81]
	v_bitop3_b32 v2, v2, v3, 7 bitop3:0x78
	v_mul_lo_u32 v1, v1, s47
	v_lshlrev_b32_e32 v192, 3, v195
	v_or_b32_e32 v40, s39, v190
	v_lshl_add_u32 v184, v2, 3, v1
	v_mov_b64_e32 v[2:3], s[80:81]
	v_and_b32_e32 v4, 24, v192
	s_movk_i32 s4, 0x60
	v_mad_i64_i32 v[2:3], s[8:9], v40, s35, v[2:3]
	v_and_or_b32 v0, v0, s4, v4
	s_ashr_i32 s4, s11, 4
	s_and_b32 s8, s4, 0x1fffff0
	s_lshr_b32 s4, s4, 1
	v_bfe_u32 v1, v195, 2, 2
	v_lshrrev_b32_e32 v194, 1, v195
	s_and_b32 s4, s4, 4
	v_and_or_b32 v1, v194, 8, v1
	s_or_b32 s4, s8, s4
	s_addk_i32 s11, 0x200
	v_or_b32_e32 v4, s4, v1
	s_ashr_i32 s4, s11, 4
	s_and_b32 s8, s4, 0x1fffff0
	s_lshr_b32 s4, s4, 1
	s_and_b32 s4, s4, 4
	s_add_i32 s48, s48, 0x1e000
	s_or_b32 s4, s8, s4
	s_lshl_b32 s51, s42, 10
	v_ashrrev_i32_e32 v181, 31, v180
	v_or_b32_e32 v1, s4, v1
	v_lshlrev_b64 v[100:101], 1, v[180:181]
	s_cmp_lg_u32 0, -1
	v_ashrrev_i32_e32 v183, 31, v182
	v_lshl_or_b32 v186, v4, 7, v0
	v_lshl_or_b32 v188, v1, 7, v0
	v_lshl_add_u64 v[0:1], s[82:83], 0, v[100:101]
	s_cselect_b32 s4, 0, 0
	v_lshlrev_b64 v[102:103], 1, v[182:183]
	v_ashrrev_i32_e32 v185, 31, v184
	s_add_i32 s49, s51, s4
	s_mov_b32 s8, m0
	s_mov_b32 m0, s49
	s_nop 0
	global_load_lds_dwordx4 v[0:1], off
	s_mov_b32 m0, s8
	v_lshl_add_u64 v[0:1], s[82:83], 0, v[102:103]
	v_lshlrev_b64 v[104:105], 1, v[184:185]
	v_ashrrev_i32_e32 v187, 31, v186
	s_add_i32 s8, s49, 0x2000
	s_mov_b32 s9, m0
	s_mov_b32 m0, s8
	s_nop 0
	global_load_lds_dwordx4 v[0:1], off
	s_mov_b32 m0, s9
	v_lshl_add_u64 v[0:1], s[82:83], 0, v[104:105]
	v_lshlrev_b64 v[106:107], 1, v[186:187]
	v_ashrrev_i32_e32 v189, 31, v188
	s_add_i32 s8, s49, 0x4000
	s_mov_b32 s9, m0
	s_mov_b32 m0, s8
	s_nop 0
	global_load_lds_dwordx4 v[0:1], off
	s_mov_b32 m0, s9
	v_lshl_add_u64 v[0:1], s[86:87], 0, v[106:107]
	s_add_i32 s11, s4, 0x12000
	v_lshlrev_b64 v[108:109], 1, v[188:189]
	s_add_i32 s51, s51, s11
	s_mov_b32 s8, m0
	s_mov_b32 m0, s51
	s_nop 0
	global_load_lds_dwordx4 v[0:1], off
	s_mov_b32 m0, s8
	v_lshl_add_u64 v[0:1], s[86:87], 0, v[108:109]
	s_add_i32 s8, s49, 0x14000
	s_mov_b32 s9, m0
	s_mov_b32 m0, s8
	s_nop 0
	global_load_lds_dwordx4 v[0:1], off
	s_mov_b32 m0, s9
	v_lshl_add_u64 v[0:1], s[94:95], 0, v[100:101]
	v_bfe_u32 v191, v195, 5, 1
	s_add_i32 s8, s49, 0x6000
	s_mov_b32 s9, m0
	s_mov_b32 m0, s8
	s_nop 0
	global_load_lds_dwordx4 v[0:1], off
	s_mov_b32 m0, s9
	v_lshl_add_u64 v[0:1], s[94:95], 0, v[102:103]
	s_add_i32 s8, s49, 0x8000
	s_mov_b32 s9, m0
	s_mov_b32 m0, s8
	s_nop 0
	global_load_lds_dwordx4 v[0:1], off
	s_mov_b32 m0, s9
	v_lshl_add_u64 v[0:1], s[94:95], 0, v[104:105]
	v_lshlrev_b32_e32 v176, 4, v191
	s_add_i32 s8, s49, 0xa000
	s_mov_b32 s9, m0
	s_mov_b32 m0, s8
	s_nop 0
	global_load_lds_dwordx4 v[0:1], off
	s_mov_b32 m0, s9
	v_lshl_add_u64 v[0:1], v[2:3], 0, v[176:177]
	global_load_dwordx4 v[2:5], v[0:1], off
	global_load_dwordx4 v[6:9], v[0:1], off offset:32
	global_load_dwordx4 v[10:13], v[0:1], off offset:64
	global_load_dwordx4 v[14:17], v[0:1], off offset:96
	global_load_dwordx4 v[18:21], v[0:1], off offset:128
	global_load_dwordx4 v[22:25], v[0:1], off offset:160
	v_and_b32_e32 v46, 32, v195
	v_ashrrev_i32_e32 v41, 31, v40
	v_lshlrev_b64 v[40:41], 7, v[40:41]
	v_or_b32_e32 v40, v40, v46
	v_lshl_add_u64 v[150:151], s[90:91], 0, v[40:41]
	v_lshl_add_u64 v[152:153], s[92:93], 0, v[40:41]
	s_mov_b32 s16, 0
	s_mov_b32 s30, s16
	s_mov_b32 s31, s16
	s_addk_i32 s10, 0x100
	s_ashr_i32 s52, s39, 6
	s_mov_b32 s17, s16
	s_mov_b32 s18, s16
	s_mov_b32 s19, s16
	s_mov_b32 s20, s16
	s_mov_b32 s21, s16
	s_mov_b32 s22, s16
	s_mov_b32 s23, s16
	s_mov_b32 s24, s16
	s_mov_b32 s25, s16
	s_mov_b32 s26, s16
	s_mov_b32 s27, s16
	s_mov_b32 s28, s16
	s_mov_b32 s29, s16
	s_lshr_b32 s56, s10, 6
	s_mov_b32 s62, 1
	s_mov_b32 s63, 4
	s_waitcnt vmcnt(5)
	v_lshlrev_b32_e32 v236, 16, v2
	v_and_b32_e32 v219, 0xffff0000, v2
	v_lshlrev_b32_e32 v218, 16, v3
	v_and_b32_e32 v158, 0xffff0000, v3
	v_lshlrev_b32_e32 v243, 16, v4
	v_and_b32_e32 v220, 0xffff0000, v4
	v_lshlrev_b32_e32 v159, 16, v5
	v_and_b32_e32 v167, 0xffff0000, v5
	global_load_dwordx4 v[2:5], v[0:1], off offset:192
	s_waitcnt vmcnt(5)
	v_lshlrev_b32_e32 v172, 16, v6
	v_and_b32_e32 v168, 0xffff0000, v6
	v_lshlrev_b32_e32 v157, 16, v7
	v_and_b32_e32 v156, 0xffff0000, v7
	v_lshlrev_b32_e32 v173, 16, v8
	v_and_b32_e32 v169, 0xffff0000, v8
	v_lshlrev_b32_e32 v163, 16, v9
	v_and_b32_e32 v161, 0xffff0000, v9
	global_load_dwordx4 v[6:9], v[0:1], off offset:224
	global_load_dwordx4 v[36:39], v[0:1], off offset:320
	global_load_dwordx4 v[42:45], v[0:1], off offset:352
	global_load_dwordx4 v[52:55], v[0:1], off offset:288
	global_load_dwordx4 v[56:59], v[0:1], off offset:256
	v_mul_f32_e32 v247, v219, v219
	v_fmac_f32_e32 v247, v236, v236
	v_fmac_f32_e32 v247, v218, v218
	v_fmac_f32_e32 v247, v158, v158
	v_fmac_f32_e32 v247, v243, v243
	v_fmac_f32_e32 v247, v220, v220
	v_fmac_f32_e32 v247, v159, v159
	v_fmac_f32_e32 v247, v167, v167
	v_fmac_f32_e32 v247, v172, v172
	v_fmac_f32_e32 v247, v168, v168
	v_fmac_f32_e32 v247, v157, v157
	v_fmac_f32_e32 v247, v156, v156
	v_fmac_f32_e32 v247, v173, v173
	v_fmac_f32_e32 v247, v169, v169
	v_fmac_f32_e32 v247, v163, v163
	v_fmac_f32_e32 v247, v161, v161
	s_waitcnt vmcnt(9)
	v_lshlrev_b32_e32 v165, 16, v10
	v_and_b32_e32 v164, 0xffff0000, v10
	v_fmac_f32_e32 v247, v165, v165
	v_lshlrev_b32_e32 v162, 16, v11
	v_fmac_f32_e32 v247, v164, v164
	v_and_b32_e32 v160, 0xffff0000, v11
	v_fmac_f32_e32 v247, v162, v162
	v_lshlrev_b32_e32 v166, 16, v12
	v_fmac_f32_e32 v247, v160, v160
	v_and_b32_e32 v212, 0xffff0000, v12
	v_fmac_f32_e32 v247, v166, v166
	v_lshlrev_b32_e32 v208, 16, v13
	v_fmac_f32_e32 v247, v212, v212
	v_and_b32_e32 v204, 0xffff0000, v13
	v_fmac_f32_e32 v247, v208, v208
	v_fmac_f32_e32 v247, v204, v204
	s_waitcnt vmcnt(8)
	v_lshlrev_b32_e32 v213, 16, v14
	v_and_b32_e32 v209, 0xffff0000, v14
	v_fmac_f32_e32 v247, v213, v213
	v_lshlrev_b32_e32 v175, 16, v15
	v_fmac_f32_e32 v247, v209, v209
	v_and_b32_e32 v171, 0xffff0000, v15
	v_fmac_f32_e32 v247, v175, v175
	v_lshlrev_b32_e32 v217, 16, v16
	v_fmac_f32_e32 v247, v171, v171
	v_and_b32_e32 v214, 0xffff0000, v16
	v_fmac_f32_e32 v247, v217, v217
	v_lshlrev_b32_e32 v206, 16, v17
	v_fmac_f32_e32 v247, v214, v214
	v_and_b32_e32 v196, 0xffff0000, v17
	v_fmac_f32_e32 v247, v206, v206
	v_fmac_f32_e32 v247, v196, v196
	s_waitcnt vmcnt(7)
	v_lshlrev_b32_e32 v215, 16, v18
	v_and_b32_e32 v210, 0xffff0000, v18
	v_fmac_f32_e32 v247, v215, v215
	v_lshlrev_b32_e32 v205, 16, v19
	v_fmac_f32_e32 v247, v210, v210
	v_and_b32_e32 v170, 0xffff0000, v19
	v_fmac_f32_e32 v247, v205, v205
	v_lshlrev_b32_e32 v216, 16, v20
	v_fmac_f32_e32 v247, v170, v170
	v_and_b32_e32 v211, 0xffff0000, v20
	v_fmac_f32_e32 v247, v216, v216
	v_lshlrev_b32_e32 v207, 16, v21
	v_fmac_f32_e32 v247, v211, v211
	v_and_b32_e32 v174, 0xffff0000, v21
	v_fmac_f32_e32 v247, v207, v207
	v_fmac_f32_e32 v247, v174, v174
	s_waitcnt vmcnt(6)
	v_lshlrev_b32_e32 v240, 16, v22
	v_and_b32_e32 v233, 0xffff0000, v22
	v_fmac_f32_e32 v247, v240, v240
	v_lshlrev_b32_e32 v227, 16, v23
	v_fmac_f32_e32 v247, v233, v233
	v_and_b32_e32 v221, 0xffff0000, v23
	v_fmac_f32_e32 v247, v227, v227
	v_lshlrev_b32_e32 v244, 16, v24
	v_fmac_f32_e32 v247, v221, v221
	v_and_b32_e32 v237, 0xffff0000, v24
	v_fmac_f32_e32 v247, v244, v244
	v_lshlrev_b32_e32 v230, 16, v25
	v_fmac_f32_e32 v247, v237, v237
	v_and_b32_e32 v224, 0xffff0000, v25
	v_fmac_f32_e32 v247, v230, v230
	v_fmac_f32_e32 v247, v224, v224
	s_waitcnt vmcnt(5)
	v_lshlrev_b32_e32 v241, 16, v2
	v_and_b32_e32 v234, 0xffff0000, v2
	v_fmac_f32_e32 v247, v241, v241
	v_lshlrev_b32_e32 v228, 16, v3
	v_fmac_f32_e32 v247, v234, v234
	v_and_b32_e32 v222, 0xffff0000, v3
	v_fmac_f32_e32 v247, v228, v228
	v_lshlrev_b32_e32 v245, 16, v4
	v_fmac_f32_e32 v247, v222, v222
	v_and_b32_e32 v238, 0xffff0000, v4
	v_fmac_f32_e32 v247, v245, v245
	v_lshlrev_b32_e32 v231, 16, v5
	v_fmac_f32_e32 v247, v238, v238
	v_and_b32_e32 v225, 0xffff0000, v5
	v_fmac_f32_e32 v247, v231, v231
	v_fmac_f32_e32 v247, v225, v225
	s_waitcnt vmcnt(4)
	v_lshlrev_b32_e32 v242, 16, v6
	v_and_b32_e32 v235, 0xffff0000, v6
	v_fmac_f32_e32 v247, v242, v242
	v_lshlrev_b32_e32 v229, 16, v7
	v_fmac_f32_e32 v247, v235, v235
	v_and_b32_e32 v223, 0xffff0000, v7
	v_fmac_f32_e32 v247, v229, v229
	v_lshlrev_b32_e32 v246, 16, v8
	v_fmac_f32_e32 v247, v223, v223
	v_add_u32_e32 v0, 0, v46
	v_and_b32_e32 v239, 0xffff0000, v8
	v_fmac_f32_e32 v247, v246, v246
	v_add_u32_e32 v248, 0x1e800, v0
	v_lshlrev_b32_e32 v232, 16, v9
	v_and_b32_e32 v226, 0xffff0000, v9
	v_fmac_f32_e32 v247, v239, v239
	ds_read_b128 v[92:95], v248
	ds_read_b128 v[88:91], v248 offset:16
	ds_read_b128 v[84:87], v248 offset:64
	ds_read_b128 v[80:83], v248 offset:80
	ds_read_b128 v[76:79], v248 offset:128
	ds_read_b128 v[72:75], v248 offset:144
	ds_read_b128 v[68:71], v248 offset:192
	ds_read_b128 v[48:51], v248 offset:208
	ds_read_b128 v[32:35], v248 offset:256
	ds_read_b128 v[28:31], v248 offset:272
	ds_read_b128 v[24:27], v248 offset:320
	ds_read_b128 v[20:23], v248 offset:336
	ds_read_b128 v[12:15], v248 offset:512
	ds_read_b128 v[8:11], v248 offset:528
	ds_read_b128 v[4:7], v248 offset:576
	ds_read_b128 v[0:3], v248 offset:592
	ds_read_b128 v[16:19], v248 offset:640
	ds_read_b128 v[96:99], v248 offset:656
	ds_read_b128 v[60:63], v248 offset:704
	ds_read_b128 v[64:67], v248 offset:720
	v_fmac_f32_e32 v247, v232, v232
	s_waitcnt vmcnt(0)
	v_lshlrev_b32_e32 v147, 16, v56
	v_lshlrev_b32_e32 v146, 16, v36
	v_fmac_f32_e32 v247, v226, v226
	v_lshlrev_b32_e32 v142, 16, v37
	v_and_b32_e32 v144, 0xffff0000, v37
	v_and_b32_e32 v149, 0xffff0000, v56
	v_and_b32_e32 v148, 0xffff0000, v36
	v_pk_mul_f32 v[36:37], v[146:147], v[146:147]
	v_lshlrev_b32_e32 v143, 16, v57
	v_and_b32_e32 v145, 0xffff0000, v57
	v_add_f32_e32 v37, v37, v247
	v_pk_mul_f32 v[56:57], v[148:149], v[148:149]
	s_waitcnt lgkmcnt(1)
	v_mov_b32_e32 v130, v60
	v_mov_b32_e32 v131, v4
	v_mov_b32_e32 v4, v61
	v_pk_mul_f32 v[60:61], v[142:143], v[142:143]
	v_add_f32_e32 v37, v57, v37
	v_mov_b32_e32 v124, v62
	v_mov_b32_e32 v125, v6
	v_mov_b32_e32 v6, v63
	v_lshlrev_b32_e32 v139, 16, v58
	v_lshlrev_b32_e32 v138, 16, v38
	v_pk_mul_f32 v[62:63], v[144:145], v[144:145]
	v_add_f32_e32 v37, v61, v37
	v_pk_mul_f32 v[46:47], v[138:139], v[138:139]
	v_and_b32_e32 v141, 0xffff0000, v58
	v_and_b32_e32 v140, 0xffff0000, v38
	v_add_f32_e32 v37, v63, v37
	v_lshlrev_b32_e32 v135, 16, v59
	v_lshlrev_b32_e32 v134, 16, v39
	v_and_b32_e32 v136, 0xffff0000, v39
	v_pk_mul_f32 v[38:39], v[140:141], v[140:141]
	v_add_f32_e32 v37, v47, v37
	v_lshlrev_b32_e32 v110, 16, v45
	v_and_b32_e32 v114, 0xffff0000, v45
	v_lshlrev_b32_e32 v116, 16, v44
	v_and_b32_e32 v120, 0xffff0000, v44
	v_pk_mul_f32 v[44:45], v[134:135], v[134:135]
	v_and_b32_e32 v137, 0xffff0000, v59
	v_add_f32_e32 v37, v39, v37
	v_lshlrev_b32_e32 v123, 16, v53
	v_and_b32_e32 v127, 0xffff0000, v53
	v_lshlrev_b32_e32 v129, 16, v52
	v_lshlrev_b32_e32 v128, 16, v42
	v_and_b32_e32 v133, 0xffff0000, v52
	v_pk_mul_f32 v[52:53], v[136:137], v[136:137]
	v_add_f32_e32 v37, v45, v37
	v_lshlrev_b32_e32 v111, 16, v55
	v_and_b32_e32 v115, 0xffff0000, v55
	v_lshlrev_b32_e32 v117, 16, v54
	v_and_b32_e32 v121, 0xffff0000, v54
	v_pk_mul_f32 v[54:55], v[128:129], v[128:129]
	v_and_b32_e32 v132, 0xffff0000, v42
	v_add_f32_e32 v37, v53, v37
	v_lshlrev_b32_e32 v122, 16, v43
	v_and_b32_e32 v126, 0xffff0000, v43
	v_pk_mul_f32 v[42:43], v[132:133], v[132:133]
	v_add_f32_e32 v37, v55, v37
	v_pk_mul_f32 v[40:41], v[122:123], v[122:123]
	v_add_f32_e32 v37, v43, v37
	v_pk_mul_f32 v[202:203], v[126:127], v[126:127]
	v_add_f32_e32 v37, v41, v37
	v_pk_mul_f32 v[154:155], v[116:117], v[116:117]
	v_add_f32_e32 v37, v203, v37
	v_pk_mul_f32 v[200:201], v[120:121], v[120:121]
	v_add_f32_e32 v37, v155, v37
	v_add_f32_e32 v37, v201, v37
	v_fmac_f32_e32 v37, v111, v111
	v_fmac_f32_e32 v37, v115, v115
	v_add_f32_e32 v36, v36, v37
	v_add_f32_e32 v36, v56, v36
	v_add_f32_e32 v36, v60, v36
	v_add_f32_e32 v36, v62, v36
	v_add_f32_e32 v36, v46, v36
	v_add_f32_e32 v36, v38, v36
	v_add_f32_e32 v41, v44, v36
	v_add_f32_e32 v41, v52, v41
	v_add_f32_e32 v41, v54, v41
	v_add_f32_e32 v41, v42, v41
	s_waitcnt lgkmcnt(0)
	v_mov_b32_e32 v112, v66
	v_mov_b32_e32 v113, v2
	v_mov_b32_e32 v2, v67
	v_mov_b32_e32 v118, v64
	v_mov_b32_e32 v119, v0
	v_mov_b32_e32 v0, v65
	global_load_dwordx4 v[64:67], v[150:151], off
	global_load_dwordx4 v[56:59], v[150:151], off offset:16
	global_load_dwordx4 v[60:63], v[152:153], off offset:16
	global_load_dwordx4 v[44:47], v[150:151], off offset:64
	global_load_dwordx4 v[36:39], v[150:151], off offset:80
	v_add_f32_e32 v150, v40, v41
	v_add_f32_e32 v155, v202, v150
	v_mov_b32_e32 v150, v114
	v_mov_b32_e32 v151, v110
	v_add_f32_e32 v154, v154, v155
	v_pk_mul_f32 v[150:151], v[150:151], v[150:151]
	v_add_f32_e32 v154, v200, v154
	v_add_f32_e32 v151, v151, v154
	v_add_f32_e32 v150, v150, v151
	v_mov_b32_e32 v151, v150
	s_nop 1
	v_permlane32_swap_b32_e32 v150, v151
	v_add_f32_e32 v150, v150, v151
	v_fmamk_f32 v150, v150, 0x3baaaaab, v197
	v_mul_f32_e32 v151, 0x4f800000, v150
	v_cmp_gt_f32_e32 vcc, s36, v150
	global_load_dwordx4 v[52:55], v[152:153], off offset:64
	global_load_dwordx4 v[40:43], v[152:153], off offset:80
	v_cndmask_b32_e32 v154, v150, v151, vcc
	v_sqrt_f32_e32 v155, v154
	v_mov_b32_e32 v150, v98
	v_mov_b32_e32 v151, v10
	v_mov_b32_e32 v10, v99
	v_add_u32_e32 v98, -1, v155
	v_fma_f32 v99, -v98, v155, v154
	v_cmp_ge_f32_e64 s[8:9], 0, v99
	v_add_u32_e32 v99, 1, v155
	s_nop 0
	v_cndmask_b32_e64 v98, v155, v98, s[8:9]
	v_fma_f32 v155, -v99, v155, v154
	v_cmp_lt_f32_e64 s[8:9], 0, v155
	v_mov_b32_e32 v155, v8
	v_mov_b32_e32 v8, v97
	v_cndmask_b32_e64 v98, v98, v99, s[8:9]
	v_mul_f32_e32 v99, 0x37800000, v98
	v_cndmask_b32_e32 v98, v98, v99, vcc
	v_cmp_class_f32_e32 vcc, v154, v198
	s_nop 1
	v_cndmask_b32_e32 v200, v98, v154, vcc
	v_div_scale_f32 v201, s[8:9], v200, v200, 1.0
	v_rcp_f32_e32 v202, v201
	v_mov_b32_e32 v154, v96
	v_div_scale_f32 v203, vcc, 1.0, v200, 1.0
	v_fma_f32 v96, -v201, v202, 1.0
	v_fmac_f32_e32 v202, v96, v202
	v_mul_f32_e32 v247, v203, v202
	v_fma_f32 v96, -v201, v247, v203
	v_fmac_f32_e32 v247, v96, v202
	global_load_dwordx4 v[96:99], v[152:153], off
	v_fma_f32 v152, -v201, v247, v203
	v_div_fmas_f32 v152, v152, v202, v247
	v_div_fixup_f32 v152, v152, v200, 1.0
	v_mul_f32_e32 v88, v88, v152
	v_mul_f32_e32 v200, v88, v243
	v_mul_f32_e32 v88, v93, v152
	v_mul_f32_e32 v93, v95, v152
	v_mul_f32_e32 v158, v93, v158
	v_mul_f32_e32 v93, v152, v48
	v_mul_f32_e32 v217, v93, v217
	v_mov_b32_e32 v93, v14
	v_mov_b32_e32 v14, v19
	v_mov_b32_e32 v19, v12
	v_mul_f32_e32 v12, v152, v32
	v_mul_f32_e32 v215, v12, v215
	v_mul_f32_e32 v12, v152, v28
	v_mul_f32_e32 v216, v12, v216
	v_mul_f32_e32 v12, v152, v33
	v_mul_f32_e32 v210, v12, v210
	v_mul_f32_e32 v12, v152, v29
	v_mul_f32_e32 v211, v12, v211
	v_mul_f32_e32 v12, v152, v34
	v_mul_f32_e32 v201, v88, v219
	v_mul_f32_e32 v88, v89, v152
	v_mul_f32_e32 v205, v12, v205
	v_mul_f32_e32 v12, v152, v30
	v_mul_f32_e32 v92, v92, v152
	v_mul_f32_e32 v202, v88, v220
	v_mul_f32_e32 v220, v152, v73
	v_mul_f32_e32 v207, v12, v207
	v_mul_f32_e32 v12, v152, v35
	v_mul_f32_e32 v153, v92, v236
	v_mul_f32_e32 v236, v152, v74
	v_mul_f32_e32 v212, v220, v212
	v_mul_f32_e32 v220, v12, v170
	v_mul_f32_e32 v12, v152, v31
	v_mul_f32_e32 v208, v236, v208
	v_mul_f32_e32 v236, v12, v174
	v_mul_f32_e32 v12, v152, v24
	v_mul_f32_e32 v243, v152, v75
	v_mul_f32_e32 v240, v12, v240
	v_mul_f32_e32 v12, v152, v20
	v_mul_f32_e32 v204, v243, v204
	v_mul_f32_e32 v243, v12, v244
	v_mul_f32_e32 v12, v152, v25
	v_mul_f32_e32 v233, v12, v233
	v_mul_f32_e32 v12, v152, v21
	v_mul_f32_e32 v92, v94, v152
	v_mul_f32_e32 v94, v152, v72
	v_mul_f32_e32 v247, v152, v68
	v_mul_f32_e32 v249, v152, v69
	v_mul_f32_e32 v250, v152, v70
	v_mul_f32_e32 v251, v152, v71
	ds_read_b128 v[68:71], v248 offset:384
	ds_read_b128 v[72:75], v248 offset:400
	v_mul_f32_e32 v237, v12, v237
	v_mul_f32_e32 v12, v152, v26
	v_mul_f32_e32 v227, v12, v227
	v_mul_f32_e32 v12, v152, v22
	v_mul_f32_e32 v230, v12, v230
	v_mul_f32_e32 v12, v152, v27
	v_mul_f32_e32 v221, v12, v221
	v_mul_f32_e32 v12, v152, v23
	v_mul_f32_e32 v224, v12, v224
	s_waitcnt lgkmcnt(1)
	v_mul_f32_e32 v12, v152, v68
	v_mul_f32_e32 v68, v12, v241
	s_waitcnt lgkmcnt(0)
	v_mul_f32_e32 v12, v152, v72
	v_mul_f32_e32 v72, v12, v245
	v_mul_f32_e32 v12, v152, v69
	v_mul_f32_e32 v80, v80, v152
	v_mul_f32_e32 v81, v81, v152
	v_mul_f32_e32 v69, v12, v234
	v_mul_f32_e32 v12, v152, v73
	v_mul_f32_e32 v203, v92, v218
	v_mul_f32_e32 v88, v90, v152
	v_mul_f32_e32 v89, v91, v152
	v_mul_f32_e32 v90, v82, v152
	v_mul_f32_e32 v91, v83, v152
	v_mul_f32_e32 v92, v76, v152
	v_mul_f32_e32 v95, v77, v152
	v_mul_f32_e32 v218, v78, v152
	v_mul_f32_e32 v219, v79, v152
	v_mul_f32_e32 v253, v80, v173
	v_mul_f32_e32 v254, v81, v169
	ds_read_b128 v[76:79], v248 offset:448
	ds_read_b128 v[80:83], v248 offset:464
	v_mul_f32_e32 v73, v12, v238
	v_mul_f32_e32 v12, v152, v70
	v_mul_f32_e32 v70, v12, v228
	v_mul_f32_e32 v12, v152, v74
	v_mul_f32_e32 v74, v12, v231
	v_mul_f32_e32 v12, v152, v71
	v_mul_f32_e32 v71, v12, v222
	v_mul_f32_e32 v12, v152, v75
	v_mul_f32_e32 v75, v12, v225
	s_waitcnt lgkmcnt(1)
	v_mul_f32_e32 v12, v152, v76
	v_mul_f32_e32 v76, v12, v242
	s_waitcnt lgkmcnt(0)
	v_mul_f32_e32 v12, v152, v80
	v_mul_f32_e32 v80, v12, v246
	v_mul_f32_e32 v12, v152, v77
	v_mul_f32_e32 v77, v12, v235
	v_mul_f32_e32 v12, v152, v81
	v_mul_f32_e32 v81, v12, v239
	v_mul_f32_e32 v12, v152, v78
	v_mul_f32_e32 v78, v12, v229
	v_mul_f32_e32 v12, v152, v82
	v_mul_f32_e32 v82, v12, v232
	v_mul_f32_e32 v12, v152, v79
	v_mul_f32_e32 v165, v92, v165
	v_mov_b32_e32 v92, v18
	v_mov_b32_e32 v18, v16
	v_mul_f32_e32 v79, v12, v223
	v_mul_f32_e32 v12, v152, v83
	v_mul_f32_e32 v83, v12, v226
	v_pk_mul_f32 v[18:19], v[152:153], v[18:19] op_sel_hi:[0,1]
	v_mov_b32_e32 v12, v17
	s_waitcnt vmcnt(7)
	v_mov_b32_e32 v28, v64
	s_waitcnt vmcnt(0)
	v_mov_b32_e32 v29, v96
	v_pk_mul_f32 v[18:19], v[18:19], v[146:147]
	v_pk_mul_f32 v[12:13], v[152:153], v[12:13] op_sel_hi:[0,1]
	v_mov_b32_e32 v34, v96
	v_mov_b32_e32 v35, v64
	v_pk_mul_f32 v[12:13], v[12:13], v[148:149]
	v_pk_mul_f32 v[34:35], v[18:19], v[34:35]
	v_pk_mul_f32 v[18:19], v[18:19], v[28:29]
	v_mov_b32_e32 v64, v97
	v_mov_b32_e32 v96, v65
	v_pk_mul_f32 v[16:17], v[152:153], v[92:93] op_sel_hi:[0,1]
	v_add_f32_e32 v28, v18, v19
	v_pk_mul_f32 v[18:19], v[12:13], v[64:65]
	v_pk_mul_f32 v[12:13], v[12:13], v[96:97]
	v_pk_mul_f32 v[16:17], v[16:17], v[142:143]
	v_sub_f32_e32 v18, v19, v18
	v_add_f32_e32 v19, v12, v13
	v_mov_b32_e32 v12, v98
	v_mov_b32_e32 v13, v66
	v_mul_f32_e32 v166, v94, v166
	v_mul_f32_e32 v164, v95, v164
	v_mov_b32_e32 v94, v66
	v_mov_b32_e32 v95, v98
	v_pk_mul_f32 v[14:15], v[152:153], v[14:15] op_sel_hi:[0,1]
	v_pk_mul_f32 v[12:13], v[16:17], v[12:13]
	v_pk_mul_f32 v[14:15], v[14:15], v[144:145]
	v_sub_f32_e32 v29, v13, v12
	v_pk_mul_f32 v[12:13], v[16:17], v[94:95]
	v_mov_b32_e32 v66, v99
	v_add_f32_e32 v16, v12, v13
	v_pk_mul_f32 v[12:13], v[14:15], v[66:67]
	v_mov_b32_e32 v98, v67
	v_pk_mul_f32 v[20:21], v[152:153], v[154:155] op_sel_hi:[0,1]
	v_sub_f32_e32 v17, v13, v12
	v_pk_mul_f32 v[12:13], v[14:15], v[98:99]
	v_pk_mul_f32 v[20:21], v[20:21], v[138:139]
	v_add_f32_e32 v14, v12, v13
	v_mov_b32_e32 v12, v60
	v_mov_b32_e32 v13, v56
	v_mul_f32_e32 v163, v90, v163
	v_mul_f32_e32 v161, v91, v161
	v_mov_b32_e32 v90, v56
	v_mov_b32_e32 v91, v60
	v_pk_mul_f32 v[8:9], v[152:153], v[8:9] op_sel_hi:[0,1]
	v_pk_mul_f32 v[12:13], v[20:21], v[12:13]
	v_pk_mul_f32 v[8:9], v[8:9], v[140:141]
	v_sub_f32_e32 v15, v13, v12
	v_pk_mul_f32 v[12:13], v[20:21], v[90:91]
	v_mov_b32_e32 v56, v61
	v_mov_b32_e32 v60, v57
	v_pk_mul_f32 v[22:23], v[152:153], v[150:151] op_sel_hi:[0,1]
	v_add_f32_e32 v20, v12, v13
	v_pk_mul_f32 v[12:13], v[8:9], v[56:57]
	v_pk_mul_f32 v[8:9], v[8:9], v[60:61]
	v_pk_mul_f32 v[22:23], v[22:23], v[134:135]
	v_sub_f32_e32 v12, v13, v12
	v_add_f32_e32 v13, v8, v9
	v_mov_b32_e32 v8, v62
	v_mov_b32_e32 v9, v58
	v_mul_f32_e32 v159, v88, v159
	v_mul_f32_e32 v167, v89, v167
	v_mov_b32_e32 v88, v58
	v_mov_b32_e32 v89, v62
	v_pk_mul_f32 v[10:11], v[152:153], v[10:11] op_sel_hi:[0,1]
	v_pk_mul_f32 v[8:9], v[22:23], v[8:9]
	v_pk_mul_f32 v[10:11], v[10:11], v[136:137]
	v_sub_f32_e32 v21, v9, v8
	v_pk_mul_f32 v[8:9], v[22:23], v[88:89]
	v_mov_b32_e32 v58, v63
	v_add_f32_e32 v22, v8, v9
	v_pk_mul_f32 v[8:9], v[10:11], v[58:59]
	v_mov_b32_e32 v62, v59
	v_pk_mul_f32 v[24:25], v[152:153], v[130:131] op_sel_hi:[0,1]
	v_sub_f32_e32 v23, v9, v8
	v_pk_mul_f32 v[8:9], v[10:11], v[62:63]
	v_mul_f32_e32 v86, v86, v152
	v_mul_f32_e32 v87, v87, v152
	v_pk_mul_f32 v[24:25], v[24:25], v[128:129]
	v_add_f32_e32 v10, v8, v9
	v_mov_b32_e32 v8, v52
	v_mov_b32_e32 v9, v44
	v_mul_f32_e32 v157, v86, v157
	v_mul_f32_e32 v156, v87, v156
	v_mov_b32_e32 v86, v44
	v_mov_b32_e32 v87, v52
	v_pk_mul_f32 v[4:5], v[152:153], v[4:5] op_sel_hi:[0,1]
	v_pk_mul_f32 v[8:9], v[24:25], v[8:9]
	v_pk_mul_f32 v[4:5], v[4:5], v[132:133]
	v_sub_f32_e32 v11, v9, v8
	v_pk_mul_f32 v[8:9], v[24:25], v[86:87]
	v_mov_b32_e32 v44, v53
	v_mov_b32_e32 v52, v45
	v_pk_mul_f32 v[30:31], v[152:153], v[124:125] op_sel_hi:[0,1]
	v_add_f32_e32 v24, v8, v9
	v_pk_mul_f32 v[8:9], v[4:5], v[44:45]
	v_pk_mul_f32 v[4:5], v[4:5], v[52:53]
	v_mul_f32_e32 v84, v84, v152
	v_mul_f32_e32 v85, v85, v152
	v_pk_mul_f32 v[30:31], v[30:31], v[122:123]
	v_sub_f32_e32 v8, v9, v8
	v_add_f32_e32 v9, v4, v5
	v_mov_b32_e32 v4, v54
	v_mov_b32_e32 v5, v46
	v_mul_f32_e32 v252, v84, v172
	v_mul_f32_e32 v168, v85, v168
	v_mov_b32_e32 v84, v46
	v_mov_b32_e32 v85, v54
	v_pk_mul_f32 v[6:7], v[152:153], v[6:7] op_sel_hi:[0,1]
	v_pk_mul_f32 v[4:5], v[30:31], v[4:5]
	v_pk_mul_f32 v[6:7], v[6:7], v[126:127]
	v_sub_f32_e32 v25, v5, v4
	v_pk_mul_f32 v[4:5], v[30:31], v[84:85]
	v_mov_b32_e32 v46, v55
	v_add_f32_e32 v30, v4, v5
	v_pk_mul_f32 v[4:5], v[6:7], v[46:47]
	v_mov_b32_e32 v54, v47
	v_pk_mul_f32 v[26:27], v[152:153], v[118:119] op_sel_hi:[0,1]
	v_sub_f32_e32 v31, v5, v4
	v_pk_mul_f32 v[4:5], v[6:7], v[54:55]
	v_pk_mul_f32 v[26:27], v[26:27], v[116:117]
	v_add_f32_e32 v6, v4, v5
	v_mov_b32_e32 v4, v40
	v_mov_b32_e32 v5, v36
	v_mul_f32_e32 v172, v152, v50
	v_mul_f32_e32 v173, v152, v51
	v_mov_b32_e32 v50, v36
	v_mov_b32_e32 v51, v40
	v_pk_mul_f32 v[0:1], v[152:153], v[0:1] op_sel_hi:[0,1]
	v_pk_mul_f32 v[4:5], v[26:27], v[4:5]
	v_pk_mul_f32 v[0:1], v[0:1], v[120:121]
	v_sub_f32_e32 v7, v5, v4
	v_pk_mul_f32 v[4:5], v[26:27], v[50:51]
	v_mov_b32_e32 v36, v41
	v_mov_b32_e32 v40, v37
	v_pk_mul_f32 v[32:33], v[152:153], v[112:113] op_sel_hi:[0,1]
	v_add_f32_e32 v26, v4, v5
	v_pk_mul_f32 v[4:5], v[0:1], v[36:37]
	v_pk_mul_f32 v[0:1], v[0:1], v[40:41]
	v_pk_mul_f32 v[32:33], v[32:33], v[110:111]
	v_sub_f32_e32 v4, v5, v4
	v_add_f32_e32 v5, v0, v1
	v_mov_b32_e32 v0, v42
	v_mov_b32_e32 v1, v38
	v_mul_f32_e32 v169, v152, v49
	v_mov_b32_e32 v48, v38
	v_mov_b32_e32 v49, v42
	v_pk_mul_f32 v[2:3], v[152:153], v[2:3] op_sel_hi:[0,1]
	v_pk_mul_f32 v[0:1], v[32:33], v[0:1]
	v_pk_mul_f32 v[2:3], v[2:3], v[114:115]
	v_sub_f32_e32 v27, v1, v0
	v_pk_mul_f32 v[0:1], v[32:33], v[48:49]
	v_mov_b32_e32 v38, v43
	v_add_f32_e32 v32, v0, v1
	v_pk_mul_f32 v[0:1], v[2:3], v[38:39]
	v_mov_b32_e32 v42, v39
	v_sub_f32_e32 v33, v1, v0
	v_pk_mul_f32 v[0:1], v[2:3], v[42:43]
	v_mul_f32_e32 v162, v218, v162
	v_mul_f32_e32 v160, v219, v160
	v_add_f32_e32 v0, v0, v1
	v_mul_f32_e32 v213, v247, v213
	v_mul_f32_e32 v209, v249, v209
	v_mul_f32_e32 v214, v169, v214
	v_mul_f32_e32 v218, v250, v175
	v_mul_f32_e32 v206, v172, v206
	v_mul_f32_e32 v219, v251, v171
	v_mul_f32_e32 v196, v173, v196
	v_sub_f32_e32 v34, v35, v34
	v_cvt_pk_bf16_f32 v172, v153, v201
	v_cvt_pk_bf16_f32 v173, v203, v158
	v_cvt_pk_bf16_f32 v174, v200, v202
	v_cvt_pk_bf16_f32 v175, v159, v167
	v_cvt_pk_bf16_f32 v168, v252, v168
	v_cvt_pk_bf16_f32 v169, v157, v156
	v_cvt_pk_bf16_f32 v170, v253, v254
	v_cvt_pk_bf16_f32 v171, v163, v161
	v_cvt_pk_bf16_f32 v164, v165, v164
	v_cvt_pk_bf16_f32 v165, v162, v160
	v_cvt_pk_bf16_f32 v166, v166, v212
	v_cvt_pk_bf16_f32 v167, v208, v204
	v_cvt_pk_bf16_f32 v160, v213, v209
	v_cvt_pk_bf16_f32 v161, v218, v219
	v_cvt_pk_bf16_f32 v162, v217, v214
	v_cvt_pk_bf16_f32 v163, v206, v196
	v_cvt_pk_bf16_f32 v156, v215, v210
	v_cvt_pk_bf16_f32 v157, v205, v220
	v_cvt_pk_bf16_f32 v158, v216, v211
	v_cvt_pk_bf16_f32 v159, v207, v236
	v_cvt_pk_bf16_f32 v152, v240, v233
	v_cvt_pk_bf16_f32 v153, v227, v221
	v_cvt_pk_bf16_f32 v154, v243, v237
	v_cvt_pk_bf16_f32 v155, v230, v224
	v_cvt_pk_bf16_f32 v148, v68, v69
	v_cvt_pk_bf16_f32 v149, v70, v71
	v_cvt_pk_bf16_f32 v150, v72, v73
	v_cvt_pk_bf16_f32 v151, v74, v75
	v_cvt_pk_bf16_f32 v144, v76, v77
	v_cvt_pk_bf16_f32 v145, v78, v79
	v_cvt_pk_bf16_f32 v146, v80, v81
	v_cvt_pk_bf16_f32 v147, v82, v83
	v_cvt_pk_bf16_f32 v140, v34, v18
	v_cvt_pk_bf16_f32 v141, v29, v17
	v_cvt_pk_bf16_f32 v142, v15, v12
	v_cvt_pk_bf16_f32 v143, v21, v23
	v_cvt_pk_bf16_f32 v136, v11, v8
	v_cvt_pk_bf16_f32 v137, v25, v31
	v_cvt_pk_bf16_f32 v138, v7, v4
	v_cvt_pk_bf16_f32 v139, v27, v33
	v_cvt_pk_bf16_f32 v132, v28, v19
	v_cvt_pk_bf16_f32 v133, v16, v14
	v_cvt_pk_bf16_f32 v134, v20, v13
	v_cvt_pk_bf16_f32 v135, v22, v10
	v_cvt_pk_bf16_f32 v128, v24, v9
	v_cvt_pk_bf16_f32 v129, v30, v6
	v_cvt_pk_bf16_f32 v130, v26, v5
	v_cvt_pk_bf16_f32 v131, v32, v0
	v_mov_b32_e32 v0, s4
	v_mad_u32_u24 v48, v190, s35, v0
	v_bfe_u32 v20, v195, 1, 3
	v_bitop3_b32 v0, v191, v194, 7 bitop3:0x78
	v_lshl_add_u32 v206, v0, 4, v48
	v_bitop3_b32 v0, v191, v20, 2 bitop3:0x36
	v_lshl_add_u32 v207, v0, 4, v48
	v_bitop3_b32 v0, v191, v20, 4 bitop3:0x36
	s_waitcnt vmcnt(0) lgkmcnt(0)
	s_barrier
	v_lshl_add_u32 v208, v0, 4, v48
	v_lshl_add_u64 v[0:1], s[96:97], 0, v[100:101]
	s_add_i32 s4, s49, 0xc000
	s_mov_b32 s8, m0
	s_mov_b32 m0, s4
	s_nop 0
	global_load_lds_dwordx4 v[0:1], off
	s_mov_b32 m0, s8
	v_lshl_add_u64 v[0:1], s[96:97], 0, v[102:103]
	s_add_i32 s4, s49, 0xe000
	s_mov_b32 s8, m0
	s_mov_b32 m0, s4
	s_nop 0
	global_load_lds_dwordx4 v[0:1], off
	s_mov_b32 m0, s8
	v_lshl_add_u64 v[0:1], s[96:97], 0, v[104:105]
	s_add_i32 s4, s49, 0x10000
	s_mov_b32 s8, m0
	s_mov_b32 m0, s4
	s_nop 0
	global_load_lds_dwordx4 v[0:1], off
	s_mov_b32 m0, s8
	v_lshl_add_u64 v[0:1], s[44:45], 0, v[106:107]
	s_add_i32 s4, s49, 0x16000
	s_mov_b32 s8, m0
	s_mov_b32 m0, s4
	s_nop 0
	global_load_lds_dwordx4 v[0:1], off
	s_mov_b32 m0, s8
	v_lshl_add_u64 v[0:1], s[44:45], 0, v[108:109]
	s_add_i32 s4, s49, 0x18000
	s_mov_b32 s8, m0
	s_mov_b32 m0, s4
	s_nop 0
	global_load_lds_dwordx4 v[0:1], off
	s_mov_b32 m0, s8
	ds_read_b128 v[0:3], v206 offset:0
	ds_read_b128 v[16:19], v206 offset:12288
	ds_read_b128 v[32:35], v207 offset:0
	ds_read_b128 v[36:39], v207 offset:12288
	ds_read_b128 v[40:43], v208 offset:0
	ds_read_b128 v[44:47], v208 offset:12288
	v_bitop3_b32 v49, v191, v20, 6 bitop3:0x36
	s_waitcnt lgkmcnt(4)
	v_lshl_add_u32 v209, v49, 4, v48
	v_mfma_f32_32x32x16_bf16 v[0:15], v[0:3], v[172:175], 0
	ds_read_b128 v[48:51], v209 offset:0
	ds_read_b128 v[52:55], v209 offset:12288
	s_waitcnt lgkmcnt(4)
	v_and_b32_e32 v194, 63, v195
	s_mov_b32 s4, 2
	v_cmp_gt_u32_e64 s[8:9], 32, v194
	v_mov_b32_e32 v211, 0
	v_mfma_f32_32x32x16_bf16 v[16:31], v[16:19], v[172:175], 0
	v_mfma_f32_32x32x16_bf16 v[0:15], v[32:35], v[168:171], v[0:15]
	ds_read_b128 v[32:35], v206 offset:128
	v_mfma_f32_32x32x16_bf16 v[16:31], v[36:39], v[168:171], v[16:31]
	ds_read_b128 v[36:39], v206 offset:12416
	s_waitcnt lgkmcnt(4)
	s_nop 0
	v_mfma_f32_32x32x16_bf16 v[0:15], v[40:43], v[164:167], v[0:15]
	ds_read_b128 v[40:43], v207 offset:128
	v_mfma_f32_32x32x16_bf16 v[16:31], v[44:47], v[164:167], v[16:31]
	ds_read_b128 v[44:47], v207 offset:12416
	s_waitcnt lgkmcnt(4)
	s_nop 0
	v_mfma_f32_32x32x16_bf16 v[0:15], v[48:51], v[160:163], v[0:15]
	ds_read_b128 v[48:51], v208 offset:128
	v_mfma_f32_32x32x16_bf16 v[16:31], v[52:55], v[160:163], v[16:31]
	ds_read_b128 v[52:55], v208 offset:12416
	s_waitcnt lgkmcnt(4)
	s_nop 0
	v_mfma_f32_32x32x16_bf16 v[0:15], v[32:35], v[156:159], v[0:15]
	ds_read_b128 v[32:35], v209 offset:128
	v_mfma_f32_32x32x16_bf16 v[16:31], v[36:39], v[156:159], v[16:31]
	ds_read_b128 v[36:39], v209 offset:12416
	s_waitcnt lgkmcnt(4)
	s_nop 0
	v_mfma_f32_32x32x16_bf16 v[0:15], v[40:43], v[152:155], v[0:15]
	ds_read_b128 v[40:43], v206 offset:256
	v_mfma_f32_32x32x16_bf16 v[16:31], v[44:47], v[152:155], v[16:31]
	ds_read_b128 v[44:47], v206 offset:12544
	s_waitcnt lgkmcnt(4)
	s_nop 0
	v_mfma_f32_32x32x16_bf16 v[0:15], v[48:51], v[148:151], v[0:15]
	ds_read_b128 v[48:51], v207 offset:256
	v_mfma_f32_32x32x16_bf16 v[16:31], v[52:55], v[148:151], v[16:31]
	ds_read_b128 v[52:55], v207 offset:12544
	s_waitcnt lgkmcnt(4)
	s_nop 0
	v_mfma_f32_32x32x16_bf16 v[0:15], v[32:35], v[144:147], v[0:15]
	ds_read_b128 v[32:35], v208 offset:256
	v_mfma_f32_32x32x16_bf16 v[16:31], v[36:39], v[144:147], v[16:31]
	ds_read_b128 v[36:39], v208 offset:12544
	s_waitcnt lgkmcnt(4)
	s_nop 0
	v_mfma_f32_32x32x16_bf16 v[0:15], v[40:43], v[140:143], v[0:15]
	ds_read_b128 v[40:43], v209 offset:256
	ds_read_b128 v[56:59], v209 offset:12544
	s_waitcnt lgkmcnt(4)
	s_waitcnt lgkmcnt(2)
	s_nop 0
	s_waitcnt lgkmcnt(0)
	s_waitcnt vmcnt(5) lgkmcnt(0)
	s_barrier
	v_mfma_f32_32x32x16_bf16 v[0:15], v[48:51], v[136:139], v[0:15]
	v_mfma_f32_32x32x16_bf16 v[16:31], v[44:47], v[140:143], v[16:31]
	v_lshlrev_b32_e32 v45, 4, v195
	v_lshlrev_b32_e32 v44, 3, v194
	v_and_b32_e32 v45, 0xc0, v45
	v_lshlrev_b32_e32 v46, 1, v195
	v_and_or_b32 v45, v44, 24, v45
	v_and_b32_e32 v46, 32, v46
	v_and_b32_e32 v44, 0x100, v44
	v_mfma_f32_32x32x16_bf16 v[0:15], v[32:35], v[132:135], v[0:15]
	v_or3_b32 v44, v45, v46, v44
	v_add_u32_e32 v196, s11, v44
	v_lshl_add_u32 v195, v190, 2, s48
	v_mfma_f32_32x32x16_bf16 v[16:31], v[52:55], v[136:139], v[16:31]
	v_mfma_f32_32x32x16_bf16 v[0:15], v[40:43], v[128:131], v[0:15]
	v_mfma_f32_32x32x16_bf16 v[16:31], v[36:39], v[132:135], v[16:31]
	s_nop 10
	v_max_f32_e32 v48, v1, v1
	v_max_f32_e32 v49, v0, v0
	v_max_f32_e32 v48, v49, v48
	v_max3_f32 v48, v48, v2, v3
	v_max3_f32 v48, v48, v4, v5
	v_max3_f32 v48, v48, v6, v7
	v_max3_f32 v48, v48, v8, v9
	v_mfma_f32_32x32x16_bf16 v[16:31], v[56:59], v[128:131], v[16:31]
	v_max3_f32 v48, v48, v10, v11
	v_max3_f32 v48, v48, v12, v13
	v_max3_f32 v48, v48, v14, v15
	v_mov_b64_e32 v[46:47], s[30:31]
	v_mov_b64_e32 v[44:45], s[28:29]
	v_mov_b64_e32 v[42:43], s[26:27]
	v_mov_b64_e32 v[40:41], s[24:25]
	s_nop 4
	v_max3_f32 v48, v48, v16, v17
	v_max3_f32 v48, v48, v18, v19
	v_max3_f32 v48, v48, v20, v21
	v_max3_f32 v48, v48, v22, v23
	v_max3_f32 v48, v48, v24, v25
	v_max3_f32 v48, v48, v26, v27
	v_max3_f32 v48, v48, v28, v29
	v_max3_f32 v48, v48, v30, v31
	v_mov_b32_e32 v49, v48
	s_nop 1
	v_permlane32_swap_b32_e32 v48, v49
	v_max_f32_e32 v49, v49, v49
	v_max_f32_e32 v48, v48, v48
	v_max_f32_e32 v48, v48, v49
	v_add_f32_e32 v49, 0x7149f2ca, v48
	v_max_f32_e32 v48, 0xf149f2ca, v48
	v_cmp_ge_f32_e32 vcc, s0, v49
	v_sub_f32_e32 v49, 0xf149f2ca, v48
	v_mul_f32_e32 v49, 0x3dd53b94, v49
	v_exp_f32_e32 v49, v49
	v_mov_b64_e32 v[38:39], s[22:23]
	v_mov_b64_e32 v[36:37], s[20:21]
	v_mov_b64_e32 v[34:35], s[18:19]
	v_mov_b64_e32 v[32:33], s[16:17]
	s_add_i32 s23, s52, 1
	s_cmp_eq_u64 vcc, exec
	s_cselect_b64 vcc, -1, 0
	v_cndmask_b32_e64 v210, v49, 1.0, vcc
	v_mov_b32_e32 v49, 0xf149f2ca
	v_cndmask_b32_e32 v204, v48, v49, vcc
	v_mul_f32_e32 v48, 0xbdd53b94, v204
	v_fmamk_f32 v0, v0, 0x3dd53b94, v48
	v_exp_f32_e32 v112, v0
	v_fmamk_f32 v0, v1, 0x3dd53b94, v48
	v_exp_f32_e32 v113, v0
	v_fmamk_f32 v0, v2, 0x3dd53b94, v48
	v_exp_f32_e32 v114, v0
	v_fmamk_f32 v0, v3, 0x3dd53b94, v48
	v_exp_f32_e32 v115, v0
	v_fmamk_f32 v0, v4, 0x3dd53b94, v48
	v_exp_f32_e32 v116, v0
	v_fmamk_f32 v0, v5, 0x3dd53b94, v48
	v_exp_f32_e32 v117, v0
	v_fmamk_f32 v0, v6, 0x3dd53b94, v48
	v_exp_f32_e32 v118, v0
	v_fmamk_f32 v0, v7, 0x3dd53b94, v48
	v_exp_f32_e32 v119, v0
	v_fmamk_f32 v0, v8, 0x3dd53b94, v48
	v_exp_f32_e32 v120, v0
	v_fmamk_f32 v0, v9, 0x3dd53b94, v48
	v_exp_f32_e32 v121, v0
	v_fmamk_f32 v0, v10, 0x3dd53b94, v48
	v_exp_f32_e32 v122, v0
	v_fmamk_f32 v0, v11, 0x3dd53b94, v48
	v_exp_f32_e32 v123, v0
	v_fmamk_f32 v0, v12, 0x3dd53b94, v48
	v_exp_f32_e32 v124, v0
	v_fmamk_f32 v0, v13, 0x3dd53b94, v48
	v_pk_fma_f32 v[110:111], v[30:31], s[68:69], v[48:49] op_sel_hi:[1,0,0]
	v_pk_fma_f32 v[108:109], v[28:29], s[68:69], v[48:49] op_sel_hi:[1,0,0]
	v_pk_fma_f32 v[106:107], v[26:27], s[68:69], v[48:49] op_sel_hi:[1,0,0]
	v_pk_fma_f32 v[104:105], v[24:25], s[68:69], v[48:49] op_sel_hi:[1,0,0]
	v_pk_fma_f32 v[102:103], v[22:23], s[68:69], v[48:49] op_sel_hi:[1,0,0]
	v_pk_fma_f32 v[100:101], v[20:21], s[68:69], v[48:49] op_sel_hi:[1,0,0]
	v_pk_fma_f32 v[98:99], v[18:19], s[68:69], v[48:49] op_sel_hi:[1,0,0]
	v_pk_fma_f32 v[96:97], v[16:17], s[68:69], v[48:49] op_sel_hi:[1,0,0]
	v_exp_f32_e32 v125, v0
	v_fmamk_f32 v0, v14, 0x3dd53b94, v48
	v_fmac_f32_e32 v48, 0x3dd53b94, v15
	v_exp_f32_e32 v126, v0
	v_exp_f32_e32 v127, v48
	v_mov_b64_e32 v[62:63], v[46:47]
	v_mov_b64_e32 v[0:1], v[32:33]
	v_mov_b64_e32 v[16:17], v[32:33]
	s_mov_b64 s[18:19], s[78:79]
	s_mov_b64 s[20:21], s[84:85]
	v_mov_b64_e32 v[60:61], v[44:45]
	v_mov_b64_e32 v[58:59], v[42:43]
	v_mov_b64_e32 v[56:57], v[40:41]
	v_mov_b64_e32 v[54:55], v[38:39]
	v_mov_b64_e32 v[52:53], v[36:37]
	v_mov_b64_e32 v[50:51], v[34:35]
	v_mov_b64_e32 v[48:49], v[32:33]
	v_mov_b64_e32 v[2:3], v[34:35]
	v_mov_b64_e32 v[4:5], v[36:37]
	v_mov_b64_e32 v[6:7], v[38:39]
	v_mov_b64_e32 v[8:9], v[40:41]
	v_mov_b64_e32 v[10:11], v[42:43]
	v_mov_b64_e32 v[12:13], v[44:45]
	v_mov_b64_e32 v[14:15], v[46:47]
	v_mov_b64_e32 v[18:19], v[34:35]
	v_mov_b64_e32 v[20:21], v[36:37]
	v_mov_b64_e32 v[22:23], v[38:39]
	v_mov_b64_e32 v[24:25], v[40:41]
	v_mov_b64_e32 v[26:27], v[42:43]
	v_mov_b64_e32 v[28:29], v[44:45]
	v_mov_b64_e32 v[30:31], v[46:47]
